# phase-0 modulation GEMV silu(c)@ada_w: serialized load-wait-per-k loop replaced by a rolling 16-deep load window (same scheme as the phase-1 bias GEMV)
# speedup vs baseline: 1.0173x; 1.0080x over previous
; __device__ __forceinline__ int obid() { int b = (int)blockIdx.x; asm volatile("" : "+s"(b)); return b; }
; __device__ __forceinline__ void phase0(const Params& P, LAS unsigned char* lds, int G) {
;     ...
;     for (int it = obid(); it < 4 * 96; it += G) { const int l = it / 96, cb = it % 96; const int col = cb * 64 + lane;
;         float a[16];
; #pragma unroll
;         for (int b = 0; b < 16; ++b) a[b] = 0.f;
;         const float* wp = P.ada_w + ((size_t)l * 1024 + wid * 128) * 6144 + col;
; #pragma unroll 16
;         for (int k = 0; k < 128; ++k) { const float w = wp[(size_t)k * 6144];
; #pragma unroll
;             for (int b = 0; b < 16; ++b) a[b] += sC[b * 1024 + wid * 128 + k] * w; }
.LBB0_845:
	s_mul_hi_i32 s6, s3, 0x2aaaaaab
	s_lshr_b32 s7, s6, 31
	s_ashr_i32 s6, s6, 4
	s_add_i32 s8, s6, s7
	s_mul_i32 s6, s8, 0x60
	s_sub_i32 s6, s3, s6
	s_ashr_i32 s9, s8, 31
	s_lshl_b32 s6, s6, 6
	s_lshl_b64 s[10:11], s[8:9], 10
	s_add_u32 s7, s10, s12
	s_addc_u32 s10, s11, s13
	s_mulk_i32 s10, 0x6000
	s_mul_hi_u32 s11, s7, 0x6000
	s_add_i32 s11, s11, s10
	s_mulk_i32 s7, 0x6000
	v_or_b32_e32 v2, s6, v67
	s_waitcnt lgkmcnt(0)
	s_add_u32 s10, s4, s7
	s_addc_u32 s11, s5, s11
	v_ashrrev_i32_e32 v3, 31, v2
	v_mov_b32_e32 v28, 0
	v_lshl_add_u64 v[70:71], v[2:3], 2, s[10:11]
	s_mov_b32 s7, 0
	v_mov_b32_e32 v29, v28
	v_mov_b32_e32 v14, v28
	v_mov_b32_e32 v15, v28
	v_mov_b32_e32 v16, v28
	v_mov_b32_e32 v17, v28
	v_mov_b32_e32 v18, v28
	v_mov_b32_e32 v19, v28
	v_mov_b32_e32 v22, v28
	v_mov_b32_e32 v23, v28
	v_mov_b32_e32 v26, v28
	v_mov_b32_e32 v27, v28
	v_mov_b32_e32 v20, v28
	v_mov_b32_e32 v21, v28
	v_mov_b32_e32 v24, v28
	v_mov_b32_e32 v25, v28
	s_movk_i32 s100, 0x1800
	s_mov_b32 s101, 0
	v_mov_b32_e32 v130, v70
	v_mov_b32_e32 v131, v71
	global_load_dword v114, v[130:131], off
	v_lshl_add_u64 v[132:133], s[100:101], 2, v[130:131]
	global_load_dword v115, v[132:133], off
	v_lshl_add_u64 v[134:135], s[100:101], 2, v[132:133]
	global_load_dword v116, v[134:135], off
	v_lshl_add_u64 v[136:137], s[100:101], 2, v[134:135]
	global_load_dword v117, v[136:137], off
	v_lshl_add_u64 v[138:139], s[100:101], 2, v[136:137]
	global_load_dword v118, v[138:139], off
	v_lshl_add_u64 v[140:141], s[100:101], 2, v[138:139]
	global_load_dword v119, v[140:141], off
	v_lshl_add_u64 v[142:143], s[100:101], 2, v[140:141]
	global_load_dword v120, v[142:143], off
	v_lshl_add_u64 v[144:145], s[100:101], 2, v[142:143]
	global_load_dword v121, v[144:145], off
	v_lshl_add_u64 v[146:147], s[100:101], 2, v[144:145]
	global_load_dword v122, v[146:147], off
	v_lshl_add_u64 v[148:149], s[100:101], 2, v[146:147]
	global_load_dword v123, v[148:149], off
	v_lshl_add_u64 v[150:151], s[100:101], 2, v[148:149]
	global_load_dword v124, v[150:151], off
	v_lshl_add_u64 v[152:153], s[100:101], 2, v[150:151]
	global_load_dword v125, v[152:153], off
	v_lshl_add_u64 v[154:155], s[100:101], 2, v[152:153]
	global_load_dword v126, v[154:155], off
	v_lshl_add_u64 v[156:157], s[100:101], 2, v[154:155]
	global_load_dword v127, v[156:157], off
	v_lshl_add_u64 v[158:159], s[100:101], 2, v[156:157]
	global_load_dword v128, v[158:159], off
	v_lshl_add_u64 v[160:161], s[100:101], 2, v[158:159]
	global_load_dword v129, v[160:161], off
.LBB0_846:
	s_cmpk_eq_i32 s7, 0x70
	s_cselect_b32 s100, 0, 0x18000
	s_mul_i32 s30, s7, 0x1800
	v_lshl_add_u64 v[90:91], s[30:31], 2, v[70:71]
	s_lshl_b32 s10, s7, 2
	s_add_i32 s10, s14, s10
	v_mov_b32_e32 v89, s10
	ds_read_b128 v[30:33], v89
	ds_read_b128 v[10:13], v89 offset:16
	ds_read_b128 v[6:9], v89 offset:32
	ds_read_b128 v[2:5], v89 offset:48
	ds_read_b128 v[34:37], v89 offset:4096
	s_waitcnt lgkmcnt(4)
	v_mov_b32_e32 v38, v30
	s_mov_b32 s10, 0x18000
	s_mov_b32 s11, s31
	s_add_i32 s7, s7, 16
	s_waitcnt lgkmcnt(0)
	v_mov_b32_e32 v39, v34
	v_mov_b32_e32 v34, v31
	s_waitcnt vmcnt(15)
	v_mov_b32_e32 v0, v114
	v_lshl_add_u64 v[130:131], s[100:101], 2, v[130:131]
	global_load_dword v114, v[130:131], off
	v_pk_fma_f32 v[92:93], v[0:1], v[38:39], v[14:15] op_sel_hi:[0,1,1]
	ds_read_b128 v[38:41], v89 offset:8192
	ds_read_b128 v[42:45], v89 offset:12288
	s_waitcnt lgkmcnt(1)
	v_mov_b32_e32 v14, v38
	s_waitcnt lgkmcnt(0)
	v_mov_b32_e32 v15, v42
	v_pk_fma_f32 v[94:95], v[0:1], v[14:15], v[16:17] op_sel_hi:[0,1,1]
	ds_read_b128 v[14:17], v89 offset:16384
	ds_read_b128 v[46:49], v89 offset:20480
	v_mov_b32_e32 v42, v39
	s_waitcnt lgkmcnt(1)
	v_mov_b32_e32 v50, v14
	s_waitcnt lgkmcnt(0)
	v_mov_b32_e32 v51, v46
	v_pk_fma_f32 v[96:97], v[0:1], v[50:51], v[18:19] op_sel_hi:[0,1,1]
	ds_read_b128 v[50:53], v89 offset:24576
	ds_read_b128 v[54:57], v89 offset:28672
	ds_read_b128 v[58:61], v89 offset:32768
	ds_read_b128 v[62:65], v89 offset:36864
	ds_read_b128 v[72:75], v89 offset:40960
	ds_read_b128 v[76:79], v89 offset:45056
	v_mov_b32_e32 v46, v15
	s_waitcnt lgkmcnt(5)
	v_mov_b32_e32 v18, v50
	s_waitcnt lgkmcnt(4)
	v_mov_b32_e32 v19, v54
	v_pk_fma_f32 v[98:99], v[0:1], v[18:19], v[22:23] op_sel_hi:[0,1,1]
	s_waitcnt lgkmcnt(3)
	v_mov_b32_e32 v18, v58
	s_waitcnt lgkmcnt(2)
	v_mov_b32_e32 v19, v62
	v_pk_fma_f32 v[26:27], v[0:1], v[18:19], v[26:27] op_sel_hi:[0,1,1]
	s_waitcnt lgkmcnt(1)
	v_mov_b32_e32 v18, v72
	s_waitcnt lgkmcnt(0)
	v_mov_b32_e32 v19, v76
	v_pk_fma_f32 v[100:101], v[0:1], v[18:19], v[20:21] op_sel_hi:[0,1,1]
	ds_read_b128 v[18:21], v89 offset:49152
	ds_read_b128 v[80:83], v89 offset:53248
	v_mov_b32_e32 v54, v51
	v_mov_b32_e32 v62, v59
	v_mov_b32_e32 v76, v73
	s_waitcnt lgkmcnt(1)
	v_mov_b32_e32 v22, v18
	s_waitcnt lgkmcnt(0)
	v_mov_b32_e32 v23, v80
	v_pk_fma_f32 v[102:103], v[0:1], v[22:23], v[24:25] op_sel_hi:[0,1,1]
	ds_read_b128 v[22:25], v89 offset:57344
	ds_read_b128 v[84:87], v89 offset:61440
	v_mov_b32_e32 v80, v19
	s_waitcnt lgkmcnt(1)
	v_mov_b32_e32 v104, v22
	s_waitcnt lgkmcnt(0)
	v_mov_b32_e32 v105, v84
	v_pk_fma_f32 v[28:29], v[0:1], v[104:105], v[28:29] op_sel_hi:[0,1,1]
	v_add_co_u32_e64 v104, s[40:41], s70, v90
	v_mov_b32_e32 v84, v23
	s_nop 0
	v_addc_co_u32_e64 v105, s[40:41], 0, v91, s[40:41]
	s_waitcnt vmcnt(15)
; __device__ __forceinline__ void phase0(const Params& P, LAS unsigned char* lds, int G) {
;     ...
;         for (int k = 0; k < 128; ++k) { const float w = wp[(size_t)k * 6144];
; #pragma unroll
;             for (int b = 0; b < 16; ++b) a[b] += sC[b * 1024 + wid * 128 + k] * w; }
	v_mov_b32_e32 v0, v115
	v_lshl_add_u64 v[132:133], s[100:101], 2, v[132:133]
	global_load_dword v115, v[132:133], off
	v_pk_fma_f32 v[22:23], v[0:1], v[84:85], v[28:29] op_sel_hi:[0,1,1]
	v_add_co_u32_e64 v28, s[40:41], s71, v90
	v_pk_fma_f32 v[30:31], v[0:1], v[34:35], v[92:93] op_sel_hi:[0,1,1]
	s_nop 0
	v_addc_co_u32_e64 v29, s[40:41], 0, v91, s[40:41]
	v_pk_fma_f32 v[34:35], v[0:1], v[42:43], v[94:95] op_sel_hi:[0,1,1]
	v_pk_fma_f32 v[14:15], v[0:1], v[46:47], v[96:97] op_sel_hi:[0,1,1]
	v_pk_fma_f32 v[38:39], v[0:1], v[54:55], v[98:99] op_sel_hi:[0,1,1]
	v_pk_fma_f32 v[26:27], v[0:1], v[62:63], v[26:27] op_sel_hi:[0,1,1]
	v_pk_fma_f32 v[42:43], v[0:1], v[76:77], v[100:101] op_sel_hi:[0,1,1]
	v_pk_fma_f32 v[18:19], v[0:1], v[80:81], v[102:103] op_sel_hi:[0,1,1]
	v_mov_b32_e32 v28, v32
	v_mov_b32_e32 v29, v36
	v_mov_b32_e32 v36, v33
	s_waitcnt vmcnt(15)
	v_mov_b32_e32 v0, v116
	v_lshl_add_u64 v[134:135], s[100:101], 2, v[134:135]
	global_load_dword v116, v[134:135], off
	v_pk_fma_f32 v[28:29], v[0:1], v[28:29], v[30:31] op_sel_hi:[0,1,1]
	v_mov_b32_e32 v30, v40
	v_mov_b32_e32 v31, v44
	v_pk_fma_f32 v[30:31], v[0:1], v[30:31], v[34:35] op_sel_hi:[0,1,1]
	v_mov_b32_e32 v34, v16
	v_mov_b32_e32 v35, v48
	v_pk_fma_f32 v[14:15], v[0:1], v[34:35], v[14:15] op_sel_hi:[0,1,1]
	v_mov_b32_e32 v34, v52
	v_mov_b32_e32 v35, v56
	v_pk_fma_f32 v[34:35], v[0:1], v[34:35], v[38:39] op_sel_hi:[0,1,1]
	v_mov_b32_e32 v38, v60
	v_mov_b32_e32 v39, v64
	v_pk_fma_f32 v[26:27], v[0:1], v[38:39], v[26:27] op_sel_hi:[0,1,1]
	v_mov_b32_e32 v38, v74
	v_mov_b32_e32 v39, v78
	v_pk_fma_f32 v[42:43], v[0:1], v[38:39], v[42:43] op_sel_hi:[0,1,1]
	v_mov_b32_e32 v38, v20
	v_mov_b32_e32 v39, v82
	v_pk_fma_f32 v[46:47], v[0:1], v[38:39], v[18:19] op_sel_hi:[0,1,1]
	v_mov_b32_e32 v18, v24
	v_mov_b32_e32 v19, v86
	v_pk_fma_f32 v[22:23], v[0:1], v[18:19], v[22:23] op_sel_hi:[0,1,1]
	v_add_co_u32_e64 v18, s[40:41], s29, v90
	v_mov_b32_e32 v48, v17
	s_nop 0
	v_addc_co_u32_e64 v19, s[40:41], 0, v91, s[40:41]
	v_mov_b32_e32 v44, v41
	v_mov_b32_e32 v56, v53
	v_mov_b32_e32 v64, v61
	v_mov_b32_e32 v78, v75
	v_mov_b32_e32 v82, v21
	v_mov_b32_e32 v86, v25
	v_mov_b32_e32 v20, v10
	s_waitcnt vmcnt(15)
	v_mov_b32_e32 v0, v117
	v_lshl_add_u64 v[136:137], s[100:101], 2, v[136:137]
	global_load_dword v117, v[136:137], off
	v_pk_fma_f32 v[18:19], v[0:1], v[36:37], v[28:29] op_sel_hi:[0,1,1]
	v_pk_fma_f32 v[36:37], v[0:1], v[48:49], v[14:15] op_sel_hi:[0,1,1]
	v_add_co_u32_e64 v14, s[40:41], s10, v90
	v_pk_fma_f32 v[38:39], v[0:1], v[44:45], v[30:31] op_sel_hi:[0,1,1]
	s_nop 0
	v_addc_co_u32_e64 v15, s[40:41], 0, v91, s[40:41]
	v_pk_fma_f32 v[34:35], v[0:1], v[56:57], v[34:35] op_sel_hi:[0,1,1]
	v_pk_fma_f32 v[32:33], v[0:1], v[64:65], v[26:27] op_sel_hi:[0,1,1]
	v_pk_fma_f32 v[30:31], v[0:1], v[78:79], v[42:43] op_sel_hi:[0,1,1]
	v_pk_fma_f32 v[28:29], v[0:1], v[82:83], v[46:47] op_sel_hi:[0,1,1]
	v_pk_fma_f32 v[26:27], v[0:1], v[86:87], v[22:23] op_sel_hi:[0,1,1]
	ds_read_b128 v[14:17], v89 offset:4112
	s_add_i32 s10, s30, 0x7800
	s_waitcnt lgkmcnt(0)
	v_mov_b32_e32 v21, v14
	v_mov_b32_e32 v14, v11
	s_waitcnt vmcnt(15)
	v_mov_b32_e32 v0, v118
	v_lshl_add_u64 v[138:139], s[100:101], 2, v[138:139]
	global_load_dword v118, v[138:139], off
	v_pk_fma_f32 v[84:85], v[0:1], v[20:21], v[18:19] op_sel_hi:[0,1,1]
	ds_read_b128 v[18:21], v89 offset:8208
	ds_read_b128 v[22:25], v89 offset:12304
	s_waitcnt lgkmcnt(1)
	v_mov_b32_e32 v40, v18
	s_waitcnt lgkmcnt(0)
	v_mov_b32_e32 v41, v22
	v_pk_fma_f32 v[86:87], v[0:1], v[40:41], v[38:39] op_sel_hi:[0,1,1]
	ds_read_b128 v[38:41], v89 offset:16400
	ds_read_b128 v[42:45], v89 offset:20496
	v_mov_b32_e32 v22, v19
	s_waitcnt lgkmcnt(1)
	v_mov_b32_e32 v46, v38
	s_waitcnt lgkmcnt(0)
	v_mov_b32_e32 v47, v42
	v_pk_fma_f32 v[90:91], v[0:1], v[46:47], v[36:37] op_sel_hi:[0,1,1]
	ds_read_b128 v[46:49], v89 offset:24592
	ds_read_b128 v[50:53], v89 offset:28688
	v_mov_b32_e32 v42, v39
	s_waitcnt lgkmcnt(1)
	v_mov_b32_e32 v36, v46
	s_waitcnt lgkmcnt(0)
	v_mov_b32_e32 v37, v50
	v_pk_fma_f32 v[92:93], v[0:1], v[36:37], v[34:35] op_sel_hi:[0,1,1]
	ds_read_b128 v[34:37], v89 offset:32784
	ds_read_b128 v[54:57], v89 offset:36880
	v_mov_b32_e32 v50, v47
	s_waitcnt lgkmcnt(1)
	v_mov_b32_e32 v58, v34
	s_waitcnt lgkmcnt(0)
	v_mov_b32_e32 v59, v54
	v_pk_fma_f32 v[94:95], v[0:1], v[58:59], v[32:33] op_sel_hi:[0,1,1]
	ds_read_b128 v[58:61], v89 offset:40976
	ds_read_b128 v[62:65], v89 offset:45072
	v_mov_b32_e32 v54, v35
	s_waitcnt lgkmcnt(1)
	v_mov_b32_e32 v32, v58
	s_waitcnt lgkmcnt(0)
	v_mov_b32_e32 v33, v62
	v_pk_fma_f32 v[96:97], v[0:1], v[32:33], v[30:31] op_sel_hi:[0,1,1]
	ds_read_b128 v[30:33], v89 offset:49168
	ds_read_b128 v[72:75], v89 offset:53264
	v_mov_b32_e32 v62, v59
	s_waitcnt lgkmcnt(1)
	v_mov_b32_e32 v76, v30
	s_waitcnt lgkmcnt(0)
	v_mov_b32_e32 v77, v72
	v_pk_fma_f32 v[28:29], v[0:1], v[76:77], v[28:29] op_sel_hi:[0,1,1]
	ds_read_b128 v[76:79], v89 offset:57360
	ds_read_b128 v[80:83], v89 offset:61456
	v_mov_b32_e32 v72, v31
	s_waitcnt lgkmcnt(1)
	v_mov_b32_e32 v98, v76
	s_waitcnt lgkmcnt(0)
	v_mov_b32_e32 v99, v80
	v_pk_fma_f32 v[26:27], v[0:1], v[98:99], v[26:27] op_sel_hi:[0,1,1]
	v_lshl_add_u64 v[98:99], s[10:11], 2, v[70:71]
	s_add_i32 s10, s30, 0x9000
	v_mov_b32_e32 v80, v77
	v_lshl_add_u64 v[30:31], s[10:11], 2, v[70:71]
	s_add_i32 s10, s30, 0xa800
	s_waitcnt vmcnt(15)
; __device__ __forceinline__ void phase0(const Params& P, LAS unsigned char* lds, int G) {
;     ...
;         for (int k = 0; k < 128; ++k) { const float w = wp[(size_t)k * 6144];
; #pragma unroll
;             for (int b = 0; b < 16; ++b) a[b] += sC[b * 1024 + wid * 128 + k] * w; }
	v_mov_b32_e32 v0, v119
	v_lshl_add_u64 v[140:141], s[100:101], 2, v[140:141]
	global_load_dword v119, v[140:141], off
	v_pk_fma_f32 v[10:11], v[0:1], v[14:15], v[84:85] op_sel_hi:[0,1,1]
	v_pk_fma_f32 v[14:15], v[0:1], v[22:23], v[86:87] op_sel_hi:[0,1,1]
	v_pk_fma_f32 v[18:19], v[0:1], v[42:43], v[90:91] op_sel_hi:[0,1,1]
	v_pk_fma_f32 v[22:23], v[0:1], v[50:51], v[92:93] op_sel_hi:[0,1,1]
	v_pk_fma_f32 v[34:35], v[0:1], v[54:55], v[94:95] op_sel_hi:[0,1,1]
	v_pk_fma_f32 v[38:39], v[0:1], v[62:63], v[96:97] op_sel_hi:[0,1,1]
	v_pk_fma_f32 v[28:29], v[0:1], v[72:73], v[28:29] op_sel_hi:[0,1,1]
	v_pk_fma_f32 v[26:27], v[0:1], v[80:81], v[26:27] op_sel_hi:[0,1,1]
	v_mov_b32_e32 v30, v12
	v_mov_b32_e32 v31, v16
	v_mov_b32_e32 v16, v13
	s_waitcnt vmcnt(15)
	v_mov_b32_e32 v0, v120
	v_lshl_add_u64 v[142:143], s[100:101], 2, v[142:143]
	global_load_dword v120, v[142:143], off
	v_pk_fma_f32 v[10:11], v[0:1], v[30:31], v[10:11] op_sel_hi:[0,1,1]
	v_mov_b32_e32 v30, v20
	v_mov_b32_e32 v31, v24
	v_pk_fma_f32 v[14:15], v[0:1], v[30:31], v[14:15] op_sel_hi:[0,1,1]
	v_mov_b32_e32 v30, v40
	v_mov_b32_e32 v31, v44
	v_pk_fma_f32 v[18:19], v[0:1], v[30:31], v[18:19] op_sel_hi:[0,1,1]
	v_mov_b32_e32 v30, v48
	v_mov_b32_e32 v31, v52
	v_pk_fma_f32 v[22:23], v[0:1], v[30:31], v[22:23] op_sel_hi:[0,1,1]
	v_mov_b32_e32 v30, v36
	v_mov_b32_e32 v31, v56
	v_pk_fma_f32 v[30:31], v[0:1], v[30:31], v[34:35] op_sel_hi:[0,1,1]
	v_mov_b32_e32 v34, v60
	v_mov_b32_e32 v35, v64
	v_pk_fma_f32 v[34:35], v[0:1], v[34:35], v[38:39] op_sel_hi:[0,1,1]
	v_mov_b32_e32 v38, v32
	v_mov_b32_e32 v39, v74
	v_pk_fma_f32 v[28:29], v[0:1], v[38:39], v[28:29] op_sel_hi:[0,1,1]
	v_mov_b32_e32 v38, v78
	v_mov_b32_e32 v39, v82
	v_pk_fma_f32 v[26:27], v[0:1], v[38:39], v[26:27] op_sel_hi:[0,1,1]
	v_lshl_add_u64 v[38:39], s[10:11], 2, v[70:71]
	s_add_i32 s10, s30, 0xc000
	v_mov_b32_e32 v24, v21
	v_mov_b32_e32 v44, v41
	v_mov_b32_e32 v52, v49
	v_mov_b32_e32 v56, v37
	v_mov_b32_e32 v64, v61
	v_mov_b32_e32 v74, v33
	v_mov_b32_e32 v82, v79
	s_waitcnt vmcnt(15)
	v_mov_b32_e32 v0, v121
	v_lshl_add_u64 v[144:145], s[100:101], 2, v[144:145]
	global_load_dword v121, v[144:145], off
	v_pk_fma_f32 v[16:17], v[0:1], v[16:17], v[10:11] op_sel_hi:[0,1,1]
	v_lshl_add_u64 v[10:11], s[10:11], 2, v[70:71]
	v_pk_fma_f32 v[24:25], v[0:1], v[24:25], v[14:15] op_sel_hi:[0,1,1]
	v_pk_fma_f32 v[38:39], v[0:1], v[44:45], v[18:19] op_sel_hi:[0,1,1]
	v_pk_fma_f32 v[40:41], v[0:1], v[52:53], v[22:23] op_sel_hi:[0,1,1]
	v_pk_fma_f32 v[46:47], v[0:1], v[56:57], v[30:31] op_sel_hi:[0,1,1]
	v_pk_fma_f32 v[76:77], v[0:1], v[64:65], v[34:35] op_sel_hi:[0,1,1]
	v_pk_fma_f32 v[58:59], v[0:1], v[74:75], v[28:29] op_sel_hi:[0,1,1]
	v_pk_fma_f32 v[54:55], v[0:1], v[82:83], v[26:27] op_sel_hi:[0,1,1]
	ds_read_b128 v[10:13], v89 offset:4128
	v_mov_b32_e32 v14, v6
	s_add_i32 s10, s30, 0xd800
	s_waitcnt lgkmcnt(0)
	v_mov_b32_e32 v15, v10
	v_mov_b32_e32 v10, v7
	s_waitcnt vmcnt(15)
	v_mov_b32_e32 v0, v122
	v_lshl_add_u64 v[146:147], s[100:101], 2, v[146:147]
	global_load_dword v122, v[146:147], off
	v_pk_fma_f32 v[56:57], v[0:1], v[14:15], v[16:17] op_sel_hi:[0,1,1]
	ds_read_b128 v[14:17], v89 offset:8224
	ds_read_b128 v[18:21], v89 offset:12320
	s_waitcnt lgkmcnt(1)
	v_mov_b32_e32 v22, v14
	s_waitcnt lgkmcnt(0)
	v_mov_b32_e32 v23, v18
	v_pk_fma_f32 v[60:61], v[0:1], v[22:23], v[24:25] op_sel_hi:[0,1,1]
	ds_read_b128 v[22:25], v89 offset:16416
	ds_read_b128 v[26:29], v89 offset:20512
	v_mov_b32_e32 v18, v15
	s_waitcnt lgkmcnt(1)
	v_mov_b32_e32 v30, v22
	s_waitcnt lgkmcnt(0)
	v_mov_b32_e32 v31, v26
	v_pk_fma_f32 v[62:63], v[0:1], v[30:31], v[38:39] op_sel_hi:[0,1,1]
	ds_read_b128 v[30:33], v89 offset:24608
	ds_read_b128 v[34:37], v89 offset:28704
	v_mov_b32_e32 v26, v23
	s_waitcnt lgkmcnt(1)
	v_mov_b32_e32 v38, v30
	s_waitcnt lgkmcnt(0)
	v_mov_b32_e32 v39, v34
	v_pk_fma_f32 v[64:65], v[0:1], v[38:39], v[40:41] op_sel_hi:[0,1,1]
	ds_read_b128 v[38:41], v89 offset:32800
	ds_read_b128 v[42:45], v89 offset:36896
	v_mov_b32_e32 v34, v31
	s_waitcnt lgkmcnt(1)
	v_mov_b32_e32 v48, v38
	s_waitcnt lgkmcnt(0)
	v_mov_b32_e32 v49, v42
	v_pk_fma_f32 v[72:73], v[0:1], v[48:49], v[46:47] op_sel_hi:[0,1,1]
	ds_read_b128 v[46:49], v89 offset:40992
	ds_read_b128 v[50:53], v89 offset:45088
	v_mov_b32_e32 v42, v39
	s_waitcnt lgkmcnt(1)
	v_mov_b32_e32 v74, v46
	s_waitcnt lgkmcnt(0)
	v_mov_b32_e32 v75, v50
	v_pk_fma_f32 v[74:75], v[0:1], v[74:75], v[76:77] op_sel_hi:[0,1,1]
	ds_read_b128 v[76:79], v89 offset:49184
	ds_read_b128 v[80:83], v89 offset:53280
	v_mov_b32_e32 v50, v47
	s_waitcnt lgkmcnt(1)
	v_mov_b32_e32 v84, v76
	s_waitcnt lgkmcnt(0)
	v_mov_b32_e32 v85, v80
	v_pk_fma_f32 v[58:59], v[0:1], v[84:85], v[58:59] op_sel_hi:[0,1,1]
	ds_read_b128 v[84:87], v89 offset:57376
	ds_read_b128 v[90:93], v89 offset:61472
	v_mov_b32_e32 v80, v77
	s_waitcnt lgkmcnt(1)
	v_mov_b32_e32 v94, v84
	s_waitcnt lgkmcnt(0)
	v_mov_b32_e32 v95, v90
	v_pk_fma_f32 v[54:55], v[0:1], v[94:95], v[54:55] op_sel_hi:[0,1,1]
	v_lshl_add_u64 v[94:95], s[10:11], 2, v[70:71]
	s_add_i32 s10, s30, 0xf000
	v_mov_b32_e32 v90, v85
	v_lshl_add_u64 v[38:39], s[10:11], 2, v[70:71]
	s_add_i32 s10, s30, 0x10800
	s_waitcnt vmcnt(15)
	v_mov_b32_e32 v0, v123
	v_lshl_add_u64 v[148:149], s[100:101], 2, v[148:149]
	global_load_dword v123, v[148:149], off
	v_pk_fma_f32 v[6:7], v[0:1], v[10:11], v[56:57] op_sel_hi:[0,1,1]
	v_pk_fma_f32 v[10:11], v[0:1], v[18:19], v[60:61] op_sel_hi:[0,1,1]
	v_pk_fma_f32 v[14:15], v[0:1], v[26:27], v[62:63] op_sel_hi:[0,1,1]
	v_pk_fma_f32 v[18:19], v[0:1], v[34:35], v[64:65] op_sel_hi:[0,1,1]
	v_pk_fma_f32 v[22:23], v[0:1], v[42:43], v[72:73] op_sel_hi:[0,1,1]
	v_pk_fma_f32 v[26:27], v[0:1], v[50:51], v[74:75] op_sel_hi:[0,1,1]
	v_pk_fma_f32 v[30:31], v[0:1], v[80:81], v[58:59] op_sel_hi:[0,1,1]
	v_pk_fma_f32 v[34:35], v[0:1], v[90:91], v[54:55] op_sel_hi:[0,1,1]
	v_mov_b32_e32 v38, v8
	v_mov_b32_e32 v39, v12
	v_mov_b32_e32 v12, v9
	s_waitcnt vmcnt(15)
; __device__ __forceinline__ void phase0(const Params& P, LAS unsigned char* lds, int G) {
;     ...
;         for (int k = 0; k < 128; ++k) { const float w = wp[(size_t)k * 6144];
; #pragma unroll
;             for (int b = 0; b < 16; ++b) a[b] += sC[b * 1024 + wid * 128 + k] * w; }
	v_mov_b32_e32 v0, v124
	v_lshl_add_u64 v[150:151], s[100:101], 2, v[150:151]
	global_load_dword v124, v[150:151], off
	v_pk_fma_f32 v[6:7], v[0:1], v[38:39], v[6:7] op_sel_hi:[0,1,1]
	v_mov_b32_e32 v38, v16
	v_mov_b32_e32 v39, v20
	v_pk_fma_f32 v[38:39], v[0:1], v[38:39], v[10:11] op_sel_hi:[0,1,1]
	v_mov_b32_e32 v10, v24
	v_mov_b32_e32 v11, v28
	v_pk_fma_f32 v[14:15], v[0:1], v[10:11], v[14:15] op_sel_hi:[0,1,1]
	v_mov_b32_e32 v10, v32
	v_mov_b32_e32 v11, v36
	v_pk_fma_f32 v[18:19], v[0:1], v[10:11], v[18:19] op_sel_hi:[0,1,1]
	v_mov_b32_e32 v10, v40
	v_mov_b32_e32 v11, v44
	v_pk_fma_f32 v[42:43], v[0:1], v[10:11], v[22:23] op_sel_hi:[0,1,1]
	v_mov_b32_e32 v10, v48
	v_mov_b32_e32 v11, v52
	v_pk_fma_f32 v[46:47], v[0:1], v[10:11], v[26:27] op_sel_hi:[0,1,1]
	v_mov_b32_e32 v10, v78
	v_mov_b32_e32 v11, v82
	v_pk_fma_f32 v[30:31], v[0:1], v[10:11], v[30:31] op_sel_hi:[0,1,1]
	v_mov_b32_e32 v10, v86
	v_mov_b32_e32 v11, v92
	v_pk_fma_f32 v[34:35], v[0:1], v[10:11], v[34:35] op_sel_hi:[0,1,1]
	v_lshl_add_u64 v[10:11], s[10:11], 2, v[70:71]
	s_add_i32 s10, s30, 0x12000
	v_mov_b32_e32 v20, v17
	v_mov_b32_e32 v28, v25
	v_mov_b32_e32 v36, v33
	v_mov_b32_e32 v44, v41
	v_mov_b32_e32 v52, v49
	v_mov_b32_e32 v82, v79
	v_mov_b32_e32 v92, v87
	s_waitcnt vmcnt(15)
	v_mov_b32_e32 v0, v125
	v_lshl_add_u64 v[152:153], s[100:101], 2, v[152:153]
	global_load_dword v125, v[152:153], off
	v_pk_fma_f32 v[10:11], v[0:1], v[12:13], v[6:7] op_sel_hi:[0,1,1]
	v_lshl_add_u64 v[6:7], s[10:11], 2, v[70:71]
	v_pk_fma_f32 v[26:27], v[0:1], v[20:21], v[38:39] op_sel_hi:[0,1,1]
	v_pk_fma_f32 v[22:23], v[0:1], v[28:29], v[14:15] op_sel_hi:[0,1,1]
	v_pk_fma_f32 v[20:21], v[0:1], v[36:37], v[18:19] op_sel_hi:[0,1,1]
	v_pk_fma_f32 v[18:19], v[0:1], v[44:45], v[42:43] op_sel_hi:[0,1,1]
	v_pk_fma_f32 v[52:53], v[0:1], v[52:53], v[46:47] op_sel_hi:[0,1,1]
	v_pk_fma_f32 v[50:51], v[0:1], v[82:83], v[30:31] op_sel_hi:[0,1,1]
	v_pk_fma_f32 v[72:73], v[0:1], v[92:93], v[34:35] op_sel_hi:[0,1,1]
	ds_read_b128 v[6:9], v89 offset:4144
	v_mov_b32_e32 v12, v2
	s_add_i32 s10, s30, 0x13800
	s_waitcnt lgkmcnt(0)
	v_mov_b32_e32 v13, v6
	v_mov_b32_e32 v6, v3
	s_waitcnt vmcnt(15)
	v_mov_b32_e32 v0, v126
	v_lshl_add_u64 v[154:155], s[100:101], 2, v[154:155]
	global_load_dword v126, v[154:155], off
	v_pk_fma_f32 v[74:75], v[0:1], v[12:13], v[10:11] op_sel_hi:[0,1,1]
	ds_read_b128 v[10:13], v89 offset:8240
	ds_read_b128 v[14:17], v89 offset:12336
	ds_read_b128 v[34:37], v89 offset:16432
	ds_read_b128 v[42:45], v89 offset:20528
	ds_read_b128 v[38:41], v89 offset:24624
	ds_read_b128 v[46:49], v89 offset:28720
	s_waitcnt lgkmcnt(5)
	v_mov_b32_e32 v24, v10
	s_waitcnt lgkmcnt(4)
	v_mov_b32_e32 v25, v14
	v_pk_fma_f32 v[76:77], v[0:1], v[24:25], v[26:27] op_sel_hi:[0,1,1]
	ds_read_b128 v[26:29], v89 offset:32816
	ds_read_b128 v[30:33], v89 offset:36912
	s_waitcnt lgkmcnt(5)
	v_mov_b32_e32 v24, v34
	s_waitcnt lgkmcnt(4)
	v_mov_b32_e32 v25, v42
	v_pk_fma_f32 v[78:79], v[0:1], v[24:25], v[22:23] op_sel_hi:[0,1,1]
	s_waitcnt lgkmcnt(3)
	v_mov_b32_e32 v22, v38
	s_waitcnt lgkmcnt(2)
	v_mov_b32_e32 v23, v46
	v_pk_fma_f32 v[80:81], v[0:1], v[22:23], v[20:21] op_sel_hi:[0,1,1]
	s_waitcnt lgkmcnt(1)
	v_mov_b32_e32 v20, v26
	s_waitcnt lgkmcnt(0)
	v_mov_b32_e32 v21, v30
	v_pk_fma_f32 v[82:83], v[0:1], v[20:21], v[18:19] op_sel_hi:[0,1,1]
	ds_read_b128 v[18:21], v89 offset:41008
	ds_read_b128 v[22:25], v89 offset:45104
	v_mov_b32_e32 v14, v11
	v_mov_b32_e32 v42, v35
	v_mov_b32_e32 v46, v39
	s_waitcnt lgkmcnt(1)
	v_mov_b32_e32 v54, v18
	s_waitcnt lgkmcnt(0)
	v_mov_b32_e32 v55, v22
	v_pk_fma_f32 v[84:85], v[0:1], v[54:55], v[52:53] op_sel_hi:[0,1,1]
	ds_read_b128 v[54:57], v89 offset:49200
	ds_read_b128 v[62:65], v89 offset:53296
	v_mov_b32_e32 v30, v27
	v_mov_b32_e32 v22, v19
	s_waitcnt lgkmcnt(1)
	v_mov_b32_e32 v52, v54
	s_waitcnt lgkmcnt(0)
	v_mov_b32_e32 v53, v62
	v_pk_fma_f32 v[86:87], v[0:1], v[52:53], v[50:51] op_sel_hi:[0,1,1]
	ds_read_b128 v[50:53], v89 offset:57392
	ds_read_b128 v[58:61], v89 offset:61488
	v_mov_b32_e32 v62, v55
	s_waitcnt lgkmcnt(1)
; __device__ __forceinline__ void phase0(const Params& P, LAS unsigned char* lds, int G) {
;     ...
;         for (int k = 0; k < 128; ++k) { const float w = wp[(size_t)k * 6144];
; #pragma unroll
;             for (int b = 0; b < 16; ++b) a[b] += sC[b * 1024 + wid * 128 + k] * w; }
; #pragma unroll
;         for (int b = 0; b < 16; ++b) red[(wid * 16 + b) * 64 + lane] = a[b];
;         __syncthreads();
;         for (int o = tid; o < 1024; o += NTHR) { const int b = o >> 6, ln = o & 63; float s = 0.f;
; #pragma unroll
;             for (int w = 0; w < 8; ++w) s += red[(w * 16 + b) * 64 + ln];
;             MOD[((size_t)l * 16 + b) * 6144 + cb * 64 + ln] = s + P.ada_b[l * 6144 + cb * 64 + ln]; }
	v_mov_b32_e32 v90, v50
	s_waitcnt lgkmcnt(0)
	v_mov_b32_e32 v91, v58
	v_pk_fma_f32 v[72:73], v[0:1], v[90:91], v[72:73] op_sel_hi:[0,1,1]
	v_lshl_add_u64 v[90:91], s[10:11], 2, v[70:71]
	s_add_i32 s10, s30, 0x15000
	v_mov_b32_e32 v58, v51
	v_lshl_add_u64 v[34:35], s[10:11], 2, v[70:71]
	s_add_i32 s30, s30, 0x16800
	s_cmpk_eq_i32 s7, 0x80
	s_waitcnt vmcnt(15)
	v_mov_b32_e32 v0, v127
	v_lshl_add_u64 v[156:157], s[100:101], 2, v[156:157]
	global_load_dword v127, v[156:157], off
	v_pk_fma_f32 v[2:3], v[0:1], v[6:7], v[74:75] op_sel_hi:[0,1,1]
	v_pk_fma_f32 v[6:7], v[0:1], v[14:15], v[76:77] op_sel_hi:[0,1,1]
	v_pk_fma_f32 v[10:11], v[0:1], v[42:43], v[78:79] op_sel_hi:[0,1,1]
	v_pk_fma_f32 v[14:15], v[0:1], v[46:47], v[80:81] op_sel_hi:[0,1,1]
	v_pk_fma_f32 v[26:27], v[0:1], v[30:31], v[82:83] op_sel_hi:[0,1,1]
	v_pk_fma_f32 v[18:19], v[0:1], v[22:23], v[84:85] op_sel_hi:[0,1,1]
	v_pk_fma_f32 v[22:23], v[0:1], v[62:63], v[86:87] op_sel_hi:[0,1,1]
	v_pk_fma_f32 v[30:31], v[0:1], v[58:59], v[72:73] op_sel_hi:[0,1,1]
	v_mov_b32_e32 v34, v4
	v_mov_b32_e32 v35, v8
	v_mov_b32_e32 v8, v5
	s_waitcnt vmcnt(15)
	v_mov_b32_e32 v0, v128
	v_lshl_add_u64 v[158:159], s[100:101], 2, v[158:159]
	global_load_dword v128, v[158:159], off
	v_pk_fma_f32 v[34:35], v[0:1], v[34:35], v[2:3] op_sel_hi:[0,1,1]
	v_mov_b32_e32 v2, v12
	v_mov_b32_e32 v3, v16
	v_pk_fma_f32 v[38:39], v[0:1], v[2:3], v[6:7] op_sel_hi:[0,1,1]
	v_mov_b32_e32 v2, v36
	v_mov_b32_e32 v3, v44
	v_pk_fma_f32 v[42:43], v[0:1], v[2:3], v[10:11] op_sel_hi:[0,1,1]
	v_mov_b32_e32 v2, v40
	v_mov_b32_e32 v3, v48
	v_pk_fma_f32 v[46:47], v[0:1], v[2:3], v[14:15] op_sel_hi:[0,1,1]
	v_mov_b32_e32 v2, v28
	v_mov_b32_e32 v3, v32
	v_pk_fma_f32 v[26:27], v[0:1], v[2:3], v[26:27] op_sel_hi:[0,1,1]
	v_mov_b32_e32 v2, v20
	v_mov_b32_e32 v3, v24
	v_pk_fma_f32 v[10:11], v[0:1], v[2:3], v[18:19] op_sel_hi:[0,1,1]
	v_mov_b32_e32 v2, v56
	v_mov_b32_e32 v3, v64
	v_pk_fma_f32 v[6:7], v[0:1], v[2:3], v[22:23] op_sel_hi:[0,1,1]
	v_mov_b32_e32 v2, v52
	v_mov_b32_e32 v3, v60
	v_lshl_add_u64 v[14:15], s[30:31], 2, v[70:71]
	v_pk_fma_f32 v[2:3], v[0:1], v[2:3], v[30:31] op_sel_hi:[0,1,1]
	v_mov_b32_e32 v16, v13
	v_mov_b32_e32 v44, v37
	v_mov_b32_e32 v48, v41
	v_mov_b32_e32 v32, v29
	v_mov_b32_e32 v24, v21
	v_mov_b32_e32 v64, v57
	v_mov_b32_e32 v60, v53
	s_waitcnt vmcnt(15)
	v_mov_b32_e32 v0, v129
	v_lshl_add_u64 v[160:161], s[100:101], 2, v[160:161]
	global_load_dword v129, v[160:161], off
	v_pk_fma_f32 v[14:15], v[0:1], v[8:9], v[34:35] op_sel_hi:[0,1,1]
	v_pk_fma_f32 v[16:17], v[0:1], v[16:17], v[38:39] op_sel_hi:[0,1,1]
	v_pk_fma_f32 v[18:19], v[0:1], v[44:45], v[42:43] op_sel_hi:[0,1,1]
	v_pk_fma_f32 v[22:23], v[0:1], v[48:49], v[46:47] op_sel_hi:[0,1,1]
	v_pk_fma_f32 v[26:27], v[0:1], v[32:33], v[26:27] op_sel_hi:[0,1,1]
	v_pk_fma_f32 v[20:21], v[0:1], v[24:25], v[10:11] op_sel_hi:[0,1,1]
	v_pk_fma_f32 v[24:25], v[0:1], v[64:65], v[6:7] op_sel_hi:[0,1,1]
	v_pk_fma_f32 v[28:29], v[0:1], v[60:61], v[2:3] op_sel_hi:[0,1,1]
	s_cbranch_scc0 .LBB0_846
	s_waitcnt vmcnt(0)
	v_add_u32_e32 v0, s15, v88
	ds_write2st64_b32 v0, v14, v15 offset1:1
	ds_write2st64_b32 v0, v16, v17 offset0:2 offset1:3
	ds_write2st64_b32 v0, v18, v19 offset0:4 offset1:5
	ds_write2st64_b32 v0, v22, v23 offset0:6 offset1:7
	ds_write2st64_b32 v0, v26, v27 offset0:8 offset1:9
	ds_write2st64_b32 v0, v20, v21 offset0:10 offset1:11
	ds_write2st64_b32 v0, v24, v25 offset0:12 offset1:13
	ds_write2st64_b32 v0, v28, v29 offset0:14 offset1:15
	s_waitcnt lgkmcnt(0)
	s_barrier
	s_and_saveexec_b64 s[10:11], vcc
	s_cbranch_execz .LBB0_844
	v_readlane_b32 s16, v255, 29
	v_readlane_b32 s17, v255, 30
	s_load_dwordx2 s[16:17], s[16:17], 0x38
	s_mul_i32 s7, s8, 0x1800
	s_add_i32 s18, s7, s6
	v_or_b32_e32 v2, s18, v67
	s_ashr_i32 s7, s6, 31
	v_ashrrev_i32_e32 v3, 31, v2
	s_lshl_b64 s[8:9], s[8:9], 4
	s_waitcnt lgkmcnt(0)
	v_lshl_add_u64 v[2:3], v[2:3], 2, s[16:17]
	v_lshl_add_u64 v[4:5], s[6:7], 2, v[68:69]
	s_mov_b64 s[6:7], 0
	v_mov_b32_e32 v0, v66
